# v007 + batched GEMM2 final epilogue (all 16 gb loads up front)
# baseline (speedup 1.0000x reference)
; __device__ __forceinline__ unsigned pk2(float lo, float hi) { return __builtin_bit_cast(unsigned, __builtin_convertvector((f32x2){lo, hi}, bf16x2_t)); }
;     __device__ __forceinline__ void operator()(f32x4 (&acc)[2][2][4][2], const pg8::Unit& u, int wr, int wc, int fr, int fq) const {
;     ...
;         for (int ai = 0; ai < 2; ++ai)
; #pragma unroll
;             for (int m = 0; m < 4; ++m) {
;                 const size_t off = (size_t)(row0 + ai * 128 + m * 16) * DM + col0;
; #pragma unroll
;                 for (int bj = 0; bj < 2; ++bj) {
;                     const u32x4 gb = *(const u32x4*)(GB + off + bj * 128);
;                     const f32x4 v0 = acc[ai][bj][m][0], v1 = acc[ai][bj][m][1];
;                     u32x4 w;
;                     w.x = pk2(v0[0] * bflo(gb.x), v0[1] * bfhi(gb.x)); w.y = pk2(v0[2] * bflo(gb.y), v0[3] * bfhi(gb.y));
;                     w.z = pk2(v1[0] * bflo(gb.z), v1[1] * bfhi(gb.z)); w.w = pk2(v1[2] * bflo(gb.w), v1[3] * bfhi(gb.w));
;                     *(u32x4*)((char*)MG + tiled_off(row0 + ai * 128 + m * 16, col0 + bj * 128)) = w;
;                 }
.LBB0_459:
	s_add_i32 s55, s53, s74
	v_or_b32_e32 v2, s55, v140
	s_or_b32 s66, s82, s75
	v_or_b32_e32 v150, s66, v142
	v_ashrrev_i32_e32 v3, 31, v2
	v_ashrrev_i32_e32 v151, 31, v150
	v_lshlrev_b64 v[138:139], 13, v[2:3]
	v_lshl_add_u64 v[146:147], s[16:17], 0, v[138:139]
	v_lshlrev_b64 v[138:139], 1, v[150:151]
	v_lshl_add_u64 v[152:153], v[146:147], 0, v[138:139]
	global_load_dwordx4 v[160:163], v[152:153], off
	global_load_dwordx4 v[164:167], v[152:153], off offset:256
	v_lshl_add_u64 v[242:243], v[152:153], 0, s[40:41]
	global_load_dwordx4 v[168:171], v[242:243], off
	global_load_dwordx4 v[172:175], v[242:243], off offset:256
	v_lshl_add_u64 v[242:243], v[152:153], 0, s[42:43]
	global_load_dwordx4 v[176:179], v[242:243], off
	global_load_dwordx4 v[180:183], v[242:243], off offset:256
	v_lshl_add_u64 v[242:243], v[152:153], 0, s[44:45]
	global_load_dwordx4 v[184:187], v[242:243], off
	global_load_dwordx4 v[188:191], v[242:243], off offset:256
	v_lshl_add_u64 v[242:243], v[152:153], 0, s[8:9]
	global_load_dwordx4 v[192:195], v[242:243], off
	global_load_dwordx4 v[196:199], v[242:243], off offset:256
	v_lshl_add_u64 v[242:243], v[152:153], 0, s[46:47]
	global_load_dwordx4 v[200:203], v[242:243], off
	global_load_dwordx4 v[204:207], v[242:243], off offset:256
	v_lshl_add_u64 v[242:243], v[152:153], 0, s[48:49]
	global_load_dwordx4 v[212:215], v[242:243], off
	global_load_dwordx4 v[216:219], v[242:243], off offset:256
	v_lshl_add_u64 v[242:243], v[152:153], 0, s[50:51]
	global_load_dwordx4 v[220:223], v[242:243], off
	global_load_dwordx4 v[224:227], v[242:243], off offset:256
	s_bfe_u32 s53, s66, 0x10005
	s_ashr_i32 s67, s55, 1
	s_ashr_i32 s55, s66, 6
	s_and_b32 s68, s67, 0xffffffc0
	s_or_b32 s66, s53, s77
	v_lshlrev_b32_e32 v0, 1, v150
	s_lshl_b32 s71, s66, 10
	s_add_i32 s66, s68, s55
	v_lshlrev_b32_e32 v150, 6, v2
	v_lshlrev_b32_e32 v151, 2, v2
	v_and_b32_e32 v3, 48, v0
	s_ashr_i32 s67, s66, 31
	v_and_b32_e32 v0, 32, v151
	v_and_or_b32 v156, v150, s76, v3
	s_lshl_b64 s[66:67], s[66:67], 14
	s_add_u32 s66, s30, s66
	v_bitop3_b32 v157, v156, s71, v0 bitop3:0xde
	s_addc_u32 s67, s31, s67
	s_or_b32 s70, s55, 2
	s_add_i32 s68, s68, s70
	s_ashr_i32 s69, s68, 31
	s_lshl_b64 s[68:69], s[68:69], 14
	s_add_u32 s68, s30, s68
	s_addc_u32 s69, s31, s69
	s_waitcnt vmcnt(15)
	v_lshlrev_b32_e32 v228, 16, v160
	v_and_b32_e32 v229, 0xffff0000, v160
	v_lshlrev_b32_e32 v230, 16, v161
	v_and_b32_e32 v231, 0xffff0000, v161
	v_lshlrev_b32_e32 v232, 16, v162
	v_and_b32_e32 v233, 0xffff0000, v162
	v_lshlrev_b32_e32 v234, 16, v163
	v_and_b32_e32 v235, 0xffff0000, v163
	v_pk_mul_f32 v[128:129], v[128:129], v[228:229]
	v_pk_mul_f32 v[130:131], v[130:131], v[230:231]
	v_pk_mul_f32 v[124:125], v[124:125], v[232:233]
	v_pk_mul_f32 v[126:127], v[126:127], v[234:235]
	v_mov_b32_e32 v240, v157
	v_cvt_pk_bf16_f32 v236, v128, v129
	v_cvt_pk_bf16_f32 v237, v130, v131
	v_cvt_pk_bf16_f32 v238, v124, v125
	v_cvt_pk_bf16_f32 v239, v126, v127
	global_store_dwordx4 v240, v[236:239], s[66:67]
	s_waitcnt vmcnt(15)
	v_lshlrev_b32_e32 v228, 16, v164
	v_and_b32_e32 v229, 0xffff0000, v164
	v_lshlrev_b32_e32 v230, 16, v165
	v_and_b32_e32 v231, 0xffff0000, v165
	v_lshlrev_b32_e32 v232, 16, v166
	v_and_b32_e32 v233, 0xffff0000, v166
	v_lshlrev_b32_e32 v234, 16, v167
	v_and_b32_e32 v235, 0xffff0000, v167
	v_pk_mul_f32 v[120:121], v[120:121], v[228:229]
	v_pk_mul_f32 v[122:123], v[122:123], v[230:231]
	v_pk_mul_f32 v[116:117], v[116:117], v[232:233]
	v_pk_mul_f32 v[118:119], v[118:119], v[234:235]
	v_cvt_pk_bf16_f32 v236, v120, v121
	v_cvt_pk_bf16_f32 v237, v122, v123
	v_cvt_pk_bf16_f32 v238, v116, v117
	v_cvt_pk_bf16_f32 v239, v118, v119
	global_store_dwordx4 v240, v[236:239], s[68:69]
	s_waitcnt vmcnt(15)
	v_lshlrev_b32_e32 v228, 16, v168
	v_and_b32_e32 v229, 0xffff0000, v168
	v_lshlrev_b32_e32 v230, 16, v169
	v_and_b32_e32 v231, 0xffff0000, v169
	v_lshlrev_b32_e32 v232, 16, v170
	v_and_b32_e32 v233, 0xffff0000, v170
	v_lshlrev_b32_e32 v234, 16, v171
	v_and_b32_e32 v235, 0xffff0000, v171
	v_pk_mul_f32 v[112:113], v[112:113], v[228:229]
	v_pk_mul_f32 v[114:115], v[114:115], v[230:231]
	v_pk_mul_f32 v[108:109], v[108:109], v[232:233]
	v_pk_mul_f32 v[110:111], v[110:111], v[234:235]
	v_add_u32_e32 v240, 0x800, v157
	v_cvt_pk_bf16_f32 v236, v112, v113
	v_cvt_pk_bf16_f32 v237, v114, v115
	v_cvt_pk_bf16_f32 v238, v108, v109
	v_cvt_pk_bf16_f32 v239, v110, v111
	global_store_dwordx4 v240, v[236:239], s[66:67]
	s_waitcnt vmcnt(15)
	v_lshlrev_b32_e32 v228, 16, v172
	v_and_b32_e32 v229, 0xffff0000, v172
	v_lshlrev_b32_e32 v230, 16, v173
	v_and_b32_e32 v231, 0xffff0000, v173
	v_lshlrev_b32_e32 v232, 16, v174
	v_and_b32_e32 v233, 0xffff0000, v174
	v_lshlrev_b32_e32 v234, 16, v175
	v_and_b32_e32 v235, 0xffff0000, v175
	v_pk_mul_f32 v[104:105], v[104:105], v[228:229]
	v_pk_mul_f32 v[106:107], v[106:107], v[230:231]
	v_pk_mul_f32 v[100:101], v[100:101], v[232:233]
	v_pk_mul_f32 v[102:103], v[102:103], v[234:235]
	v_cvt_pk_bf16_f32 v236, v104, v105
	v_cvt_pk_bf16_f32 v237, v106, v107
	v_cvt_pk_bf16_f32 v238, v100, v101
	v_cvt_pk_bf16_f32 v239, v102, v103
	global_store_dwordx4 v240, v[236:239], s[68:69]
	s_waitcnt vmcnt(15)
	v_lshlrev_b32_e32 v228, 16, v176
	v_and_b32_e32 v229, 0xffff0000, v176
	v_lshlrev_b32_e32 v230, 16, v177
	v_and_b32_e32 v231, 0xffff0000, v177
	v_lshlrev_b32_e32 v232, 16, v178
	v_and_b32_e32 v233, 0xffff0000, v178
	v_lshlrev_b32_e32 v234, 16, v179
	v_and_b32_e32 v235, 0xffff0000, v179
	v_pk_mul_f32 v[96:97], v[96:97], v[228:229]
	v_pk_mul_f32 v[98:99], v[98:99], v[230:231]
	v_pk_mul_f32 v[92:93], v[92:93], v[232:233]
	v_pk_mul_f32 v[94:95], v[94:95], v[234:235]
	v_add_u32_e32 v240, 0x1000, v157
	v_cvt_pk_bf16_f32 v236, v96, v97
	v_cvt_pk_bf16_f32 v237, v98, v99
	v_cvt_pk_bf16_f32 v238, v92, v93
	v_cvt_pk_bf16_f32 v239, v94, v95
	global_store_dwordx4 v240, v[236:239], s[66:67]
	s_waitcnt vmcnt(15)
; __device__ __forceinline__ unsigned pk2(float lo, float hi) { return __builtin_bit_cast(unsigned, __builtin_convertvector((f32x2){lo, hi}, bf16x2_t)); }
;     __device__ __forceinline__ void operator()(f32x4 (&acc)[2][2][4][2], const pg8::Unit& u, int wr, int wc, int fr, int fq) const {
;     ...
;         for (int ai = 0; ai < 2; ++ai)
; #pragma unroll
;             for (int m = 0; m < 4; ++m) {
;                 const size_t off = (size_t)(row0 + ai * 128 + m * 16) * DM + col0;
; #pragma unroll
;                 for (int bj = 0; bj < 2; ++bj) {
;                     const u32x4 gb = *(const u32x4*)(GB + off + bj * 128);
;                     const f32x4 v0 = acc[ai][bj][m][0], v1 = acc[ai][bj][m][1];
;                     u32x4 w;
;                     w.x = pk2(v0[0] * bflo(gb.x), v0[1] * bfhi(gb.x)); w.y = pk2(v0[2] * bflo(gb.y), v0[3] * bfhi(gb.y));
;                     w.z = pk2(v1[0] * bflo(gb.z), v1[1] * bfhi(gb.z)); w.w = pk2(v1[2] * bflo(gb.w), v1[3] * bfhi(gb.w));
;                     *(u32x4*)((char*)MG + tiled_off(row0 + ai * 128 + m * 16, col0 + bj * 128)) = w;
;                 }
	v_lshlrev_b32_e32 v228, 16, v180
	v_and_b32_e32 v229, 0xffff0000, v180
	v_lshlrev_b32_e32 v230, 16, v181
	v_and_b32_e32 v231, 0xffff0000, v181
	v_lshlrev_b32_e32 v232, 16, v182
	v_and_b32_e32 v233, 0xffff0000, v182
	v_lshlrev_b32_e32 v234, 16, v183
	v_and_b32_e32 v235, 0xffff0000, v183
	v_pk_mul_f32 v[88:89], v[88:89], v[228:229]
	v_pk_mul_f32 v[90:91], v[90:91], v[230:231]
	v_pk_mul_f32 v[84:85], v[84:85], v[232:233]
	v_pk_mul_f32 v[86:87], v[86:87], v[234:235]
	v_cvt_pk_bf16_f32 v236, v88, v89
	v_cvt_pk_bf16_f32 v237, v90, v91
	v_cvt_pk_bf16_f32 v238, v84, v85
	v_cvt_pk_bf16_f32 v239, v86, v87
	global_store_dwordx4 v240, v[236:239], s[68:69]
	s_waitcnt vmcnt(15)
	v_lshlrev_b32_e32 v228, 16, v184
	v_and_b32_e32 v229, 0xffff0000, v184
	v_lshlrev_b32_e32 v230, 16, v185
	v_and_b32_e32 v231, 0xffff0000, v185
	v_lshlrev_b32_e32 v232, 16, v186
	v_and_b32_e32 v233, 0xffff0000, v186
	v_lshlrev_b32_e32 v234, 16, v187
	v_and_b32_e32 v235, 0xffff0000, v187
	v_pk_mul_f32 v[80:81], v[80:81], v[228:229]
	v_pk_mul_f32 v[82:83], v[82:83], v[230:231]
	v_pk_mul_f32 v[76:77], v[76:77], v[232:233]
	v_pk_mul_f32 v[78:79], v[78:79], v[234:235]
	v_add_u32_e32 v240, 0x1800, v157
	v_cvt_pk_bf16_f32 v236, v80, v81
	v_cvt_pk_bf16_f32 v237, v82, v83
	v_cvt_pk_bf16_f32 v238, v76, v77
	v_cvt_pk_bf16_f32 v239, v78, v79
	global_store_dwordx4 v240, v[236:239], s[66:67]
	s_waitcnt vmcnt(15)
	v_lshlrev_b32_e32 v228, 16, v188
	v_and_b32_e32 v229, 0xffff0000, v188
	v_lshlrev_b32_e32 v230, 16, v189
	v_and_b32_e32 v231, 0xffff0000, v189
	v_lshlrev_b32_e32 v232, 16, v190
	v_and_b32_e32 v233, 0xffff0000, v190
	v_lshlrev_b32_e32 v234, 16, v191
	v_and_b32_e32 v235, 0xffff0000, v191
	v_pk_mul_f32 v[72:73], v[72:73], v[228:229]
	v_pk_mul_f32 v[74:75], v[74:75], v[230:231]
	v_pk_mul_f32 v[68:69], v[68:69], v[232:233]
	v_pk_mul_f32 v[70:71], v[70:71], v[234:235]
	v_cvt_pk_bf16_f32 v236, v72, v73
	v_cvt_pk_bf16_f32 v237, v74, v75
	v_cvt_pk_bf16_f32 v238, v68, v69
	v_cvt_pk_bf16_f32 v239, v70, v71
	global_store_dwordx4 v240, v[236:239], s[68:69]
	s_waitcnt vmcnt(15)
	v_lshlrev_b32_e32 v228, 16, v192
	v_and_b32_e32 v229, 0xffff0000, v192
	v_lshlrev_b32_e32 v230, 16, v193
	v_and_b32_e32 v231, 0xffff0000, v193
	v_lshlrev_b32_e32 v232, 16, v194
	v_and_b32_e32 v233, 0xffff0000, v194
	v_lshlrev_b32_e32 v234, 16, v195
	v_and_b32_e32 v235, 0xffff0000, v195
	v_pk_mul_f32 v[64:65], v[64:65], v[228:229]
	v_pk_mul_f32 v[66:67], v[66:67], v[230:231]
	v_pk_mul_f32 v[60:61], v[60:61], v[232:233]
	v_pk_mul_f32 v[62:63], v[62:63], v[234:235]
	v_add_u32_e32 v240, 0x100000, v157
	v_cvt_pk_bf16_f32 v236, v64, v65
	v_cvt_pk_bf16_f32 v237, v66, v67
	v_cvt_pk_bf16_f32 v238, v60, v61
	v_cvt_pk_bf16_f32 v239, v62, v63
	global_store_dwordx4 v240, v[236:239], s[66:67]
	s_waitcnt vmcnt(15)
	v_lshlrev_b32_e32 v228, 16, v196
	v_and_b32_e32 v229, 0xffff0000, v196
	v_lshlrev_b32_e32 v230, 16, v197
	v_and_b32_e32 v231, 0xffff0000, v197
	v_lshlrev_b32_e32 v232, 16, v198
	v_and_b32_e32 v233, 0xffff0000, v198
	v_lshlrev_b32_e32 v234, 16, v199
	v_and_b32_e32 v235, 0xffff0000, v199
	v_pk_mul_f32 v[56:57], v[56:57], v[228:229]
	v_pk_mul_f32 v[58:59], v[58:59], v[230:231]
	v_pk_mul_f32 v[52:53], v[52:53], v[232:233]
	v_pk_mul_f32 v[54:55], v[54:55], v[234:235]
	v_cvt_pk_bf16_f32 v236, v56, v57
	v_cvt_pk_bf16_f32 v237, v58, v59
	v_cvt_pk_bf16_f32 v238, v52, v53
	v_cvt_pk_bf16_f32 v239, v54, v55
	global_store_dwordx4 v240, v[236:239], s[68:69]
	s_waitcnt vmcnt(15)
	v_lshlrev_b32_e32 v228, 16, v200
	v_and_b32_e32 v229, 0xffff0000, v200
	v_lshlrev_b32_e32 v230, 16, v201
	v_and_b32_e32 v231, 0xffff0000, v201
	v_lshlrev_b32_e32 v232, 16, v202
	v_and_b32_e32 v233, 0xffff0000, v202
	v_lshlrev_b32_e32 v234, 16, v203
	v_and_b32_e32 v235, 0xffff0000, v203
	v_pk_mul_f32 v[48:49], v[48:49], v[228:229]
	v_pk_mul_f32 v[50:51], v[50:51], v[230:231]
	v_pk_mul_f32 v[44:45], v[44:45], v[232:233]
	v_pk_mul_f32 v[46:47], v[46:47], v[234:235]
	v_add_u32_e32 v240, 0x100800, v157
	v_cvt_pk_bf16_f32 v236, v48, v49
	v_cvt_pk_bf16_f32 v237, v50, v51
	v_cvt_pk_bf16_f32 v238, v44, v45
	v_cvt_pk_bf16_f32 v239, v46, v47
	global_store_dwordx4 v240, v[236:239], s[66:67]
	s_waitcnt vmcnt(15)
; __device__ __forceinline__ unsigned pk2(float lo, float hi) { return __builtin_bit_cast(unsigned, __builtin_convertvector((f32x2){lo, hi}, bf16x2_t)); }
;     __device__ __forceinline__ void operator()(f32x4 (&acc)[2][2][4][2], const pg8::Unit& u, int wr, int wc, int fr, int fq) const {
;     ...
;         for (int ai = 0; ai < 2; ++ai)
; #pragma unroll
;             for (int m = 0; m < 4; ++m) {
;                 const size_t off = (size_t)(row0 + ai * 128 + m * 16) * DM + col0;
; #pragma unroll
;                 for (int bj = 0; bj < 2; ++bj) {
;                     const u32x4 gb = *(const u32x4*)(GB + off + bj * 128);
;                     const f32x4 v0 = acc[ai][bj][m][0], v1 = acc[ai][bj][m][1];
;                     u32x4 w;
;                     w.x = pk2(v0[0] * bflo(gb.x), v0[1] * bfhi(gb.x)); w.y = pk2(v0[2] * bflo(gb.y), v0[3] * bfhi(gb.y));
;                     w.z = pk2(v1[0] * bflo(gb.z), v1[1] * bfhi(gb.z)); w.w = pk2(v1[2] * bflo(gb.w), v1[3] * bfhi(gb.w));
;                     *(u32x4*)((char*)MG + tiled_off(row0 + ai * 128 + m * 16, col0 + bj * 128)) = w;
;                 }
	v_lshlrev_b32_e32 v228, 16, v204
	v_and_b32_e32 v229, 0xffff0000, v204
	v_lshlrev_b32_e32 v230, 16, v205
	v_and_b32_e32 v231, 0xffff0000, v205
	v_lshlrev_b32_e32 v232, 16, v206
	v_and_b32_e32 v233, 0xffff0000, v206
	v_lshlrev_b32_e32 v234, 16, v207
	v_and_b32_e32 v235, 0xffff0000, v207
	v_pk_mul_f32 v[40:41], v[40:41], v[228:229]
	v_pk_mul_f32 v[42:43], v[42:43], v[230:231]
	v_pk_mul_f32 v[36:37], v[36:37], v[232:233]
	v_pk_mul_f32 v[38:39], v[38:39], v[234:235]
	v_cvt_pk_bf16_f32 v236, v40, v41
	v_cvt_pk_bf16_f32 v237, v42, v43
	v_cvt_pk_bf16_f32 v238, v36, v37
	v_cvt_pk_bf16_f32 v239, v38, v39
	global_store_dwordx4 v240, v[236:239], s[68:69]
	s_waitcnt vmcnt(15)
	v_lshlrev_b32_e32 v228, 16, v212
	v_and_b32_e32 v229, 0xffff0000, v212
	v_lshlrev_b32_e32 v230, 16, v213
	v_and_b32_e32 v231, 0xffff0000, v213
	v_lshlrev_b32_e32 v232, 16, v214
	v_and_b32_e32 v233, 0xffff0000, v214
	v_lshlrev_b32_e32 v234, 16, v215
	v_and_b32_e32 v235, 0xffff0000, v215
	v_pk_mul_f32 v[32:33], v[32:33], v[228:229]
	v_pk_mul_f32 v[34:35], v[34:35], v[230:231]
	v_pk_mul_f32 v[28:29], v[28:29], v[232:233]
	v_pk_mul_f32 v[30:31], v[30:31], v[234:235]
	v_add_u32_e32 v240, 0x101000, v157
	v_cvt_pk_bf16_f32 v236, v32, v33
	v_cvt_pk_bf16_f32 v237, v34, v35
	v_cvt_pk_bf16_f32 v238, v28, v29
	v_cvt_pk_bf16_f32 v239, v30, v31
	global_store_dwordx4 v240, v[236:239], s[66:67]
	s_waitcnt vmcnt(15)
	v_lshlrev_b32_e32 v228, 16, v216
	v_and_b32_e32 v229, 0xffff0000, v216
	v_lshlrev_b32_e32 v230, 16, v217
	v_and_b32_e32 v231, 0xffff0000, v217
	v_lshlrev_b32_e32 v232, 16, v218
	v_and_b32_e32 v233, 0xffff0000, v218
	v_lshlrev_b32_e32 v234, 16, v219
	v_and_b32_e32 v235, 0xffff0000, v219
	v_pk_mul_f32 v[24:25], v[24:25], v[228:229]
	v_pk_mul_f32 v[26:27], v[26:27], v[230:231]
	v_pk_mul_f32 v[20:21], v[20:21], v[232:233]
	v_pk_mul_f32 v[22:23], v[22:23], v[234:235]
	v_cvt_pk_bf16_f32 v236, v24, v25
	v_cvt_pk_bf16_f32 v237, v26, v27
	v_cvt_pk_bf16_f32 v238, v20, v21
	v_cvt_pk_bf16_f32 v239, v22, v23
	global_store_dwordx4 v240, v[236:239], s[68:69]
	s_waitcnt vmcnt(15)
	v_lshlrev_b32_e32 v228, 16, v220
	v_and_b32_e32 v229, 0xffff0000, v220
	v_lshlrev_b32_e32 v230, 16, v221
	v_and_b32_e32 v231, 0xffff0000, v221
	v_lshlrev_b32_e32 v232, 16, v222
	v_and_b32_e32 v233, 0xffff0000, v222
	v_lshlrev_b32_e32 v234, 16, v223
	v_and_b32_e32 v235, 0xffff0000, v223
	v_pk_mul_f32 v[16:17], v[16:17], v[228:229]
	v_pk_mul_f32 v[18:19], v[18:19], v[230:231]
	v_pk_mul_f32 v[12:13], v[12:13], v[232:233]
	v_pk_mul_f32 v[14:15], v[14:15], v[234:235]
	v_add_u32_e32 v240, 0x101800, v157
	v_cvt_pk_bf16_f32 v236, v16, v17
	v_cvt_pk_bf16_f32 v237, v18, v19
	v_cvt_pk_bf16_f32 v238, v12, v13
	v_cvt_pk_bf16_f32 v239, v14, v15
	global_store_dwordx4 v240, v[236:239], s[66:67]
	s_waitcnt vmcnt(15)
	v_lshlrev_b32_e32 v228, 16, v224
	v_and_b32_e32 v229, 0xffff0000, v224
	v_lshlrev_b32_e32 v230, 16, v225
	v_and_b32_e32 v231, 0xffff0000, v225
	v_lshlrev_b32_e32 v232, 16, v226
	v_and_b32_e32 v233, 0xffff0000, v226
	v_lshlrev_b32_e32 v234, 16, v227
	v_and_b32_e32 v235, 0xffff0000, v227
	v_pk_mul_f32 v[8:9], v[8:9], v[228:229]
	v_pk_mul_f32 v[10:11], v[10:11], v[230:231]
	v_pk_mul_f32 v[4:5], v[4:5], v[232:233]
	v_pk_mul_f32 v[6:7], v[6:7], v[234:235]
	v_cvt_pk_bf16_f32 v236, v8, v9
	v_cvt_pk_bf16_f32 v237, v10, v11
	v_cvt_pk_bf16_f32 v238, v4, v5
	v_cvt_pk_bf16_f32 v239, v6, v7
	global_store_dwordx4 v240, v[236:239], s[68:69]
	s_andn2_b64 vcc, exec, s[0:1]
	s_mov_b64 s[0:1], -1
	s_cbranch_vccnz .LBB0_443
	s_andn2_b64 vcc, exec, s[12:13]
	s_cbranch_vccnz .LBB0_442
	s_barrier
	s_branch .LBB0_442
